# grid barrier: leader no longer bumps the (now unread) per-XCD generation word before the closing barrier; non-leaders poll the top generation directly
# baseline (speedup 1.0000x reference)
.LBB0_134:
	s_or_b64 exec, exec, s[8:9]
	s_mov_b64 s[8:9], exec
	v_mbcnt_lo_u32_b32 v0, s8, 0
	v_mbcnt_hi_u32_b32 v0, s9, v0
	v_cmp_eq_u32_e32 vcc, 0, v0
	s_waitcnt vmcnt(0)
	buffer_inv sc1
	s_and_saveexec_b64 s[10:11], vcc
	s_cbranch_execz .LBB0_136
	s_bcnt1_i32_b64 s8, s[8:9]
	v_mov_b32_e32 v0, 0x2000
	v_mov_b32_e32 v1, s8
	s_nop 0

.LBB0_250:
	s_or_b64 exec, exec, s[12:13]
	s_mov_b64 s[12:13], exec
	v_mbcnt_lo_u32_b32 v0, s12, 0
	v_mbcnt_hi_u32_b32 v0, s13, v0
	v_cmp_eq_u32_e32 vcc, 0, v0
	s_waitcnt vmcnt(0)
	buffer_inv sc1
	s_and_saveexec_b64 s[14:15], vcc
	s_cbranch_execz .LBB0_252
	s_bcnt1_i32_b64 s6, s[12:13]
	v_mov_b32_e32 v0, 0x2000
	v_mov_b32_e32 v1, s6
	s_nop 0

.LBB0_315:
	s_or_b64 exec, exec, s[12:13]
	s_mov_b64 s[12:13], exec
	v_mbcnt_lo_u32_b32 v0, s12, 0
	v_mbcnt_hi_u32_b32 v0, s13, v0
	v_cmp_eq_u32_e32 vcc, 0, v0
	s_waitcnt vmcnt(0)
	buffer_inv sc1
	s_and_saveexec_b64 s[14:15], vcc
	s_cbranch_execz .LBB0_317
	s_bcnt1_i32_b64 s12, s[12:13]
	v_mov_b32_e32 v0, 0x2000
	v_mov_b32_e32 v1, s12
	s_nop 0

.LBB0_496:
	s_or_b64 exec, exec, s[14:15]
	s_mov_b64 s[14:15], exec
	v_mbcnt_lo_u32_b32 v0, s14, 0
	v_mbcnt_hi_u32_b32 v0, s15, v0
	v_cmp_eq_u32_e32 vcc, 0, v0
	s_waitcnt vmcnt(0)
	buffer_inv sc1
	s_and_saveexec_b64 s[16:17], vcc
	s_cbranch_execz .LBB0_498
	s_bcnt1_i32_b64 s6, s[14:15]
	v_mov_b32_e32 v0, 0x2000
	v_mov_b32_e32 v1, s6
	s_nop 0

.LBB0_1024:
	s_or_b64 exec, exec, s[10:11]
	s_mov_b64 s[10:11], exec
	v_mbcnt_lo_u32_b32 v0, s10, 0
	v_mbcnt_hi_u32_b32 v0, s11, v0
	v_cmp_eq_u32_e32 vcc, 0, v0
	s_waitcnt vmcnt(0)
	buffer_inv sc1
	s_and_saveexec_b64 s[12:13], vcc
	s_cbranch_execz .LBB0_1026
	s_bcnt1_i32_b64 s10, s[10:11]
	v_mov_b32_e32 v0, 0x2000
	v_mov_b32_e32 v1, s10
	s_nop 0

.LBB0_1299:
	s_or_b64 exec, exec, s[4:5]
	s_mov_b64 s[4:5], exec
	v_mbcnt_lo_u32_b32 v16, s4, 0
	v_mbcnt_hi_u32_b32 v16, s5, v16
	v_cmp_eq_u32_e32 vcc, 0, v16
	s_waitcnt vmcnt(0)
	buffer_inv sc1
	s_and_saveexec_b64 s[10:11], vcc
	s_cbranch_execz .LBB0_1301
	s_bcnt1_i32_b64 s4, s[4:5]
	v_mov_b32_e32 v16, 0x2000
	v_mov_b32_e32 v17, s4
	s_nop 0
